# attention softmax: max-chain prefix 4->2 instructions and the '0 + p' start of the row-sum chain removed (bit-identical), on top of the SrcC-fold loop
# baseline (speedup 1.0000x reference)
; #define MFMA(a, b, c) __builtin_amdgcn_mfma_f32_32x32x16_bf16((a), (b), (c), 0, 0, 0)
; DI float fexp2(float x) { return __builtin_amdgcn_exp2f(x); }
; DI f32x16 zero16() { f32x16 z; for (int i = 0; i < 16; ++i) z[i] = 0.f; return z; }
; DI void phase_attn(const Params& p, int hf, bool skipctx, char* smem, int& rot) {
;     ...
;       f32x16 st[2]; st[0] = zero16(); st[1] = zero16();
;       {
;         bf16x8 kf[2][6];
; #pragma unroll
;         for (int kb = 0; kb < 2; ++kb)
; #pragma unroll
;           for (int ks = 0; ks < 6; ++ks) kf[kb][ks] = *(const bf16x8*)(sk + (kb * 32 + r) * KROW + (ks * 16 + h * 8) * 2);
;         __builtin_amdgcn_sched_barrier(0);
; #pragma unroll
;         for (int ks = 0; ks < 6; ++ks)
; #pragma unroll
;           for (int kb = 0; kb < 2; ++kb) st[kb] = MFMA(kf[kb][ks], qf[ks], st[kb]);
;         __builtin_amdgcn_sched_barrier(0);
;       }
;       bf16x8 vf[2][2][2];
; #pragma unroll
;       for (int kb = 0; kb < 2; ++kb)
; #pragma unroll
;         for (int s2 = 0; s2 < 2; ++s2)
; #pragma unroll
;           for (int dvb = 0; dvb < 2; ++dvb) {
;             const char* vp = sv + (dvb * 32 + r) * VROW + (kb * 32 + 16 * s2 + 4 * h) * 2;
;             const s16x4 lo = *(const s16x4*)vp, hi = *(const s16x4*)(vp + 16);
;             vf[kb][s2][dvb] = __builtin_shufflevector(lo, hi, 0, 1, 2, 3, 4, 5, 6, 7);
;           }
;       float mx = st[0][0];
; #pragma unroll
;       for (int i = 0; i < 16; ++i) { mx = fmaxf(mx, st[0][i]); mx = fmaxf(mx, st[1][i]); }
;       if (__any(mx > m_run + 8.f)) {
;         mx = fmaxf(mx, __shfl_xor(mx, 32));
;         const float m_new = fmaxf(m_run, mx);
;         const float alpha = fexp2(m_run - m_new);
;         m_run = m_new;
;         l_run *= alpha;
; #pragma unroll
;         for (int i = 0; i < 16; ++i) { o[0][i] *= alpha; o[1][i] *= alpha; }
;       }
.LBB0_797:
	s_waitcnt lgkmcnt(11)
	v_mfma_f32_32x32x16_bf16 v[48:63], v[32:35], v[64:67], v[176:191]
	s_waitcnt lgkmcnt(5)
	v_mfma_f32_32x32x16_bf16 v[32:47], v[36:39], v[64:67], v[176:191]
	v_mfma_f32_32x32x16_bf16 v[48:63], v[128:131], v[68:71], v[48:63]
	s_waitcnt lgkmcnt(4)
	v_mfma_f32_32x32x16_bf16 v[32:47], v[148:151], v[68:71], v[32:47]
	v_mfma_f32_32x32x16_bf16 v[48:63], v[132:135], v[72:75], v[48:63]
	s_waitcnt lgkmcnt(3)
	v_mfma_f32_32x32x16_bf16 v[32:47], v[152:155], v[72:75], v[32:47]
	v_mfma_f32_32x32x16_bf16 v[48:63], v[136:139], v[88:91], v[48:63]
	s_waitcnt lgkmcnt(2)
	v_mfma_f32_32x32x16_bf16 v[32:47], v[156:159], v[88:91], v[32:47]
	v_mfma_f32_32x32x16_bf16 v[48:63], v[140:143], v[96:99], v[48:63]
	s_waitcnt lgkmcnt(1)
	v_mfma_f32_32x32x16_bf16 v[32:47], v[214:217], v[96:99], v[32:47]
	v_mfma_f32_32x32x16_bf16 v[48:63], v[144:147], v[100:103], v[48:63]
	s_waitcnt lgkmcnt(0)
	v_mfma_f32_32x32x16_bf16 v[32:47], v[234:237], v[100:103], v[32:47]
	s_nop 3
	ds_read_b128 v[156:159], v211 offset:0
	ds_read_b128 v[148:151], v211 offset:32
	ds_read_b128 v[152:155], v211 offset:8704
	ds_read_b128 v[144:147], v211 offset:8736
	ds_read_b128 v[140:143], v211 offset:64
	ds_read_b128 v[136:139], v211 offset:8768
	ds_read_b128 v[132:135], v211 offset:96
	ds_read_b128 v[128:131], v211 offset:8800
	v_max3_f32 v195, v32, v48, v49
	v_max_f32_e32 v195, v195, v33
	v_max3_f32 v195, v195, v50, v34
	v_max3_f32 v195, v195, v51, v35
	v_max3_f32 v195, v195, v52, v36
	v_max3_f32 v195, v195, v53, v37
	v_max3_f32 v195, v195, v54, v38
	v_max3_f32 v195, v195, v55, v39
	v_max3_f32 v195, v195, v56, v40
	v_max3_f32 v195, v195, v57, v41
	v_max3_f32 v195, v195, v58, v42
	v_max3_f32 v195, v195, v59, v43
	v_max3_f32 v195, v195, v60, v44
	v_max3_f32 v195, v195, v61, v45
	v_max3_f32 v195, v195, v62, v46
	v_max3_f32 v217, v195, v63, v47
	v_cmp_gt_f32_e32 vcc, v217, v220
	s_cbranch_vccz .LBB0_799
	v_sub_f32_e32 v217, v217, v176
	v_cmp_lt_i32_e32 vcc, v224, v207
	s_nop 1
	v_cndmask_b32_e32 v195, v205, v224, vcc
	v_lshlrev_b32_e32 v195, 2, v195
	ds_bpermute_b32 v195, v195, v217
	s_waitcnt lgkmcnt(0)
	v_max3_f32 v195, v212, v217, v195
	v_sub_f32_e32 v200, v212, v195
	v_exp_f32_e32 v200, v200
	v_mov_b32_e32 v212, v195
	v_mul_f32_e32 v213, v213, v200
	v_pk_mul_f32 v[30:31], v[30:31], v[200:201] op_sel_hi:[1,0]
	v_pk_mul_f32 v[28:29], v[28:29], v[200:201] op_sel_hi:[1,0]
	v_pk_mul_f32 v[26:27], v[26:27], v[200:201] op_sel_hi:[1,0]
	v_pk_mul_f32 v[24:25], v[24:25], v[200:201] op_sel_hi:[1,0]
	v_pk_mul_f32 v[22:23], v[22:23], v[200:201] op_sel_hi:[1,0]
	v_pk_mul_f32 v[20:21], v[20:21], v[200:201] op_sel_hi:[1,0]
	v_pk_mul_f32 v[18:19], v[18:19], v[200:201] op_sel_hi:[1,0]
	v_pk_mul_f32 v[16:17], v[16:17], v[200:201] op_sel_hi:[1,0]
	v_pk_mul_f32 v[14:15], v[14:15], v[200:201] op_sel_hi:[1,0]
	v_pk_mul_f32 v[12:13], v[12:13], v[200:201] op_sel_hi:[1,0]
	v_pk_mul_f32 v[10:11], v[10:11], v[200:201] op_sel_hi:[1,0]
	v_pk_mul_f32 v[8:9], v[8:9], v[200:201] op_sel_hi:[1,0]
	v_pk_mul_f32 v[6:7], v[6:7], v[200:201] op_sel_hi:[1,0]
	v_pk_mul_f32 v[4:5], v[4:5], v[200:201] op_sel_hi:[1,0]
	v_pk_mul_f32 v[2:3], v[2:3], v[200:201] op_sel_hi:[1,0]
	v_pk_mul_f32 v[0:1], v[0:1], v[200:201] op_sel_hi:[1,0]
	v_add_f32_e32 v202, v195, v176
	v_sub_f32_e32 v32, v32, v202
	v_sub_f32_e32 v33, v33, v202
	v_sub_f32_e32 v34, v34, v202
	v_sub_f32_e32 v35, v35, v202
	v_sub_f32_e32 v36, v36, v202
	v_sub_f32_e32 v37, v37, v202
	v_sub_f32_e32 v38, v38, v202
	v_sub_f32_e32 v39, v39, v202
	v_sub_f32_e32 v40, v40, v202
	v_sub_f32_e32 v41, v41, v202
	v_sub_f32_e32 v42, v42, v202
	v_sub_f32_e32 v43, v43, v202
	v_sub_f32_e32 v44, v44, v202
	v_sub_f32_e32 v45, v45, v202
	v_sub_f32_e32 v46, v46, v202
	v_sub_f32_e32 v47, v47, v202
	v_sub_f32_e32 v48, v48, v202
	v_sub_f32_e32 v49, v49, v202
	v_sub_f32_e32 v50, v50, v202
	v_sub_f32_e32 v51, v51, v202
	v_sub_f32_e32 v52, v52, v202
	v_sub_f32_e32 v53, v53, v202
	v_sub_f32_e32 v54, v54, v202
	v_sub_f32_e32 v55, v55, v202
	v_sub_f32_e32 v56, v56, v202
	v_sub_f32_e32 v57, v57, v202
	v_sub_f32_e32 v58, v58, v202
	v_sub_f32_e32 v59, v59, v202
	v_sub_f32_e32 v60, v60, v202
	v_sub_f32_e32 v61, v61, v202
	v_sub_f32_e32 v62, v62, v202
	v_sub_f32_e32 v63, v63, v202
	v_sub_f32_e32 v176, 0, v195
	v_sub_f32_e32 v177, 0, v195
	v_sub_f32_e32 v178, 0, v195
	v_sub_f32_e32 v179, 0, v195
	v_sub_f32_e32 v180, 0, v195
	v_sub_f32_e32 v181, 0, v195
	v_sub_f32_e32 v182, 0, v195
	v_sub_f32_e32 v183, 0, v195
	v_sub_f32_e32 v184, 0, v195
	v_sub_f32_e32 v185, 0, v195
	v_sub_f32_e32 v186, 0, v195
	v_sub_f32_e32 v187, 0, v195
	v_sub_f32_e32 v188, 0, v195
	v_sub_f32_e32 v189, 0, v195
	v_sub_f32_e32 v190, 0, v195
	v_sub_f32_e32 v191, 0, v195
	v_mov_b32_e32 v220, 0x41000000
; #define MFMA(a, b, c) __builtin_amdgcn_mfma_f32_32x32x16_bf16((a), (b), (c), 0, 0, 0)
; DI void phase_attn(const Params& p, int hf, bool skipctx, char* smem, int& rot) {
;     ...
;       f32x16 st[2]; st[0] = zero16(); st[1] = zero16();
;       {
;         bf16x8 kf[2][6];
; #pragma unroll
;         for (int kb = 0; kb < 2; ++kb)
; #pragma unroll
;           for (int ks = 0; ks < 6; ++ks) kf[kb][ks] = *(const bf16x8*)(sk + (kb * 32 + r) * KROW + (ks * 16 + h * 8) * 2);
;         __builtin_amdgcn_sched_barrier(0);
; #pragma unroll
;         for (int ks = 0; ks < 6; ++ks)
; #pragma unroll
;           for (int kb = 0; kb < 2; ++kb) st[kb] = MFMA(kf[kb][ks], qf[ks], st[kb]);
;         __builtin_amdgcn_sched_barrier(0);
;       }
;       bf16x8 vf[2][2][2];
; #pragma unroll
;       for (int kb = 0; kb < 2; ++kb)
; #pragma unroll
;         for (int s2 = 0; s2 < 2; ++s2)
; #pragma unroll
;           for (int dvb = 0; dvb < 2; ++dvb) {
;             const char* vp = sv + (dvb * 32 + r) * VROW + (kb * 32 + 16 * s2 + 4 * h) * 2;
;             const s16x4 lo = *(const s16x4*)vp, hi = *(const s16x4*)(vp + 16);
;             vf[kb][s2][dvb] = __builtin_shufflevector(lo, hi, 0, 1, 2, 3, 4, 5, 6, 7);
;           }
;       float mx = st[0][0];
; #pragma unroll
;       for (int i = 0; i < 16; ++i) { mx = fmaxf(mx, st[0][i]); mx = fmaxf(mx, st[1][i]); }
;       if (__any(mx > m_run + 8.f)) {
;         mx = fmaxf(mx, __shfl_xor(mx, 32));
;         const float m_new = fmaxf(m_run, mx);
;         const float alpha = fexp2(m_run - m_new);
;         m_run = m_new;
;         l_run *= alpha;
; #pragma unroll
;         for (int i = 0; i < 16; ++i) { o[0][i] *= alpha; o[1][i] *= alpha; }
;       }
;       float ps = 0.f;
; #pragma unroll
;       for (int kb = 0; kb < 2; ++kb)
; #pragma unroll
;         for (int i = 0; i < 16; ++i) { const float e = fexp2(st[kb][i] - m_run); st[kb][i] = e; ps += e; }
;       l_run += ps;
; #pragma unroll
;       for (int kb = 0; kb < 2; ++kb)
; #pragma unroll
;         for (int s2 = 0; s2 < 2; ++s2) {
;           const bf16x8 pb = pack8(st[kb][8 * s2 + 0], st[kb][8 * s2 + 1], st[kb][8 * s2 + 2], st[kb][8 * s2 + 3], st[kb][8 * s2 + 4], st[kb][8 * s2 + 5], st[kb][8 * s2 + 6], st[kb][8 * s2 + 7]);
; #pragma unroll
;           for (int dvb = 0; dvb < 2; ++dvb) o[dvb] = MFMA(vf[kb][s2][dvb], pb, o[dvb]);
;         }
.LBB0_799:
	v_exp_f32_e32 v48, v48
	v_exp_f32_e32 v49, v49
	v_exp_f32_e32 v50, v50
	v_exp_f32_e32 v51, v51
	v_exp_f32_e32 v52, v52
	v_add_f32_e32 v195, v49, v48
	v_exp_f32_e32 v53, v53
	v_add_f32_e32 v195, v50, v195
	v_exp_f32_e32 v54, v54
	v_add_f32_e32 v195, v51, v195
	v_exp_f32_e32 v55, v55
	v_add_f32_e32 v195, v52, v195
	v_exp_f32_e32 v56, v56
	v_add_f32_e32 v195, v53, v195
	v_exp_f32_e32 v57, v57
	v_add_f32_e32 v195, v54, v195
	v_exp_f32_e32 v58, v58
	v_add_f32_e32 v195, v55, v195
	v_exp_f32_e32 v59, v59
	v_add_f32_e32 v195, v56, v195
	v_exp_f32_e32 v60, v60
	v_add_f32_e32 v195, v57, v195
	v_exp_f32_e32 v61, v61
	v_add_f32_e32 v195, v58, v195
	v_exp_f32_e32 v62, v62
	v_add_f32_e32 v195, v59, v195
	v_exp_f32_e32 v63, v63
	v_add_f32_e32 v195, v60, v195
	v_exp_f32_e32 v200, v32
	v_add_f32_e32 v195, v61, v195
	v_exp_f32_e32 v201, v33
	v_add_f32_e32 v32, v62, v195
	v_exp_f32_e32 v195, v34
	v_add_f32_e32 v32, v63, v32
	v_exp_f32_e32 v202, v35
	v_add_f32_e32 v32, v200, v32
	v_exp_f32_e32 v36, v36
	v_add_f32_e32 v32, v201, v32
	v_exp_f32_e32 v37, v37
	v_add_f32_e32 v32, v195, v32
	v_add_f32_e32 v32, v202, v32
	v_add_f32_e32 v32, v36, v32
	v_add_f32_e32 v203, v37, v32
	v_cvt_pk_bf16_f32 v32, v48, v49
	v_cvt_pk_bf16_f32 v33, v50, v51
	v_cvt_pk_bf16_f32 v34, v52, v53
	v_cvt_pk_bf16_f32 v35, v54, v55
	v_exp_f32_e32 v38, v38
	s_waitcnt lgkmcnt(7)
	v_mfma_f32_32x32x16_bf16 v[16:31], v[156:159], v[32:35], v[16:31]
	v_exp_f32_e32 v39, v39
	v_exp_f32_e32 v40, v40
	v_add_f32_e32 v48, v38, v203
	v_exp_f32_e32 v42, v42
	s_waitcnt lgkmcnt(5)
	v_mfma_f32_32x32x16_bf16 v[0:15], v[152:155], v[32:35], v[0:15]
	v_exp_f32_e32 v41, v41
	v_cvt_pk_bf16_f32 v32, v56, v57
	v_cvt_pk_bf16_f32 v33, v58, v59
	v_cvt_pk_bf16_f32 v34, v60, v61
	v_cvt_pk_bf16_f32 v35, v62, v63
	v_add_f32_e32 v48, v39, v48
	s_nop 0
	v_mfma_f32_32x32x16_bf16 v[16:31], v[148:151], v[32:35], v[16:31]
	v_exp_f32_e32 v43, v43
	v_add_f32_e32 v48, v40, v48
	v_exp_f32_e32 v44, v44
	v_add_f32_e32 v48, v41, v48
	s_waitcnt lgkmcnt(4)
	v_mfma_f32_32x32x16_bf16 v[0:15], v[144:147], v[32:35], v[0:15]
	v_add_f32_e32 v32, v42, v48
	v_add_f32_e32 v32, v43, v32
	v_add_f32_e32 v48, v44, v32
	v_cvt_pk_bf16_f32 v32, v200, v201
	v_cvt_pk_bf16_f32 v33, v195, v202
	v_cvt_pk_bf16_f32 v34, v36, v37
	v_cvt_pk_bf16_f32 v35, v38, v39
	v_exp_f32_e32 v36, v45
	s_waitcnt lgkmcnt(3)
	v_mfma_f32_32x32x16_bf16 v[16:31], v[140:143], v[32:35], v[16:31]
	v_exp_f32_e32 v37, v46
	v_exp_f32_e32 v38, v47
	v_add_f32_e32 v39, v36, v48
	s_waitcnt lgkmcnt(2)
	v_mfma_f32_32x32x16_bf16 v[0:15], v[136:139], v[32:35], v[0:15]
	v_add_f32_e32 v32, v37, v39
	v_add_f32_e32 v32, v38, v32
	v_add_f32_e32 v213, v213, v32
	v_cvt_pk_bf16_f32 v32, v40, v41
	v_cvt_pk_bf16_f32 v33, v42, v43
	v_cvt_pk_bf16_f32 v34, v44, v36
	v_cvt_pk_bf16_f32 v35, v37, v38
	s_waitcnt lgkmcnt(1)
	s_nop 0
	v_mfma_f32_32x32x16_bf16 v[16:31], v[132:135], v[32:35], v[16:31]
	ds_read_b128 v[36:39], v210 offset:13312
	ds_read_b128 v[132:135], v210 offset:13344
	ds_read_b128 v[136:139], v210 offset:13376
	ds_read_b128 v[140:143], v210 offset:13408
	ds_read_b128 v[144:147], v210 offset:13440
	ds_read_b128 v[148:151], v210 offset:13472
	ds_read_b128 v[40:43], v210 offset:19968
	ds_read_b128 v[152:155], v210 offset:20000
	ds_read_b128 v[156:159], v210 offset:20032
	ds_read_b128 v[234:237], v210 offset:20064
	ds_read_b128 v[238:241], v210 offset:20096
	ds_read_b128 v[242:245], v210 offset:20128
	s_waitcnt lgkmcnt(12)
	v_mfma_f32_32x32x16_bf16 v[0:15], v[128:131], v[32:35], v[0:15]
	s_waitcnt lgkmcnt(11)
	v_mfma_f32_32x32x16_bf16 v[48:63], v[36:39], v[64:67], v[176:191]
	s_waitcnt lgkmcnt(5)
	v_mfma_f32_32x32x16_bf16 v[32:47], v[40:43], v[64:67], v[176:191]
	v_mfma_f32_32x32x16_bf16 v[48:63], v[132:135], v[68:71], v[48:63]
	s_waitcnt lgkmcnt(4)
	v_mfma_f32_32x32x16_bf16 v[32:47], v[152:155], v[68:71], v[32:47]
	v_mfma_f32_32x32x16_bf16 v[48:63], v[136:139], v[72:75], v[48:63]
	s_waitcnt lgkmcnt(3)
	v_mfma_f32_32x32x16_bf16 v[32:47], v[156:159], v[72:75], v[32:47]
	v_mfma_f32_32x32x16_bf16 v[48:63], v[140:143], v[88:91], v[48:63]
	s_waitcnt lgkmcnt(2)
	v_mfma_f32_32x32x16_bf16 v[32:47], v[234:237], v[88:91], v[32:47]
	v_mfma_f32_32x32x16_bf16 v[48:63], v[144:147], v[96:99], v[48:63]
	s_waitcnt lgkmcnt(1)
	v_mfma_f32_32x32x16_bf16 v[32:47], v[238:241], v[96:99], v[32:47]
	v_mfma_f32_32x32x16_bf16 v[48:63], v[148:151], v[100:103], v[48:63]
	s_waitcnt lgkmcnt(0)
	v_mfma_f32_32x32x16_bf16 v[32:47], v[242:245], v[100:103], v[32:47]
	s_nop 3
	ds_read_b128 v[156:159], v211 offset:128
	ds_read_b128 v[148:151], v211 offset:160
	ds_read_b128 v[152:155], v211 offset:8832
	ds_read_b128 v[144:147], v211 offset:8864
	ds_read_b128 v[140:143], v211 offset:192
	ds_read_b128 v[136:139], v211 offset:8896
	ds_read_b128 v[128:131], v211 offset:224
	ds_read_b128 v[132:135], v211 offset:8928
	v_max3_f32 v195, v32, v48, v49
	v_max_f32_e32 v195, v195, v33
	v_max3_f32 v195, v195, v50, v34
	v_max3_f32 v195, v195, v51, v35
	v_max3_f32 v195, v195, v52, v36
	v_max3_f32 v195, v195, v53, v37
	v_max3_f32 v195, v195, v54, v38
	v_max3_f32 v195, v195, v55, v39
	v_max3_f32 v195, v195, v56, v40
	v_max3_f32 v195, v195, v57, v41
	v_max3_f32 v195, v195, v58, v42
	v_max3_f32 v195, v195, v59, v43
	v_max3_f32 v195, v195, v60, v44
	v_max3_f32 v195, v195, v61, v45
	v_max3_f32 v195, v195, v62, v46
	v_max3_f32 v214, v195, v63, v47
	v_cmp_gt_f32_e32 vcc, v214, v220
	s_cbranch_vccz .LBB0_801
; DI float fexp2(float x) { return __builtin_amdgcn_exp2f(x); }
; DI void phase_attn(const Params& p, int hf, bool skipctx, char* smem, int& rot) {
;     ...
;       if (__any(mx > m_run + 8.f)) {
;         mx = fmaxf(mx, __shfl_xor(mx, 32));
;         const float m_new = fmaxf(m_run, mx);
;         const float alpha = fexp2(m_run - m_new);
;         m_run = m_new;
;         l_run *= alpha;
; #pragma unroll
;         for (int i = 0; i < 16; ++i) { o[0][i] *= alpha; o[1][i] *= alpha; }
;       }
	v_sub_f32_e32 v214, v214, v176
	v_cmp_lt_i32_e32 vcc, v224, v207
	s_nop 1
	v_cndmask_b32_e32 v195, v205, v224, vcc
	v_lshlrev_b32_e32 v195, 2, v195
	ds_bpermute_b32 v195, v195, v214
	s_waitcnt lgkmcnt(0)
	v_max3_f32 v195, v212, v214, v195
	v_sub_f32_e32 v200, v212, v195
	v_exp_f32_e32 v200, v200
	v_mov_b32_e32 v212, v195
	v_mul_f32_e32 v213, v213, v200
	v_pk_mul_f32 v[30:31], v[30:31], v[200:201] op_sel_hi:[1,0]
	v_pk_mul_f32 v[28:29], v[28:29], v[200:201] op_sel_hi:[1,0]
	v_pk_mul_f32 v[26:27], v[26:27], v[200:201] op_sel_hi:[1,0]
	v_pk_mul_f32 v[24:25], v[24:25], v[200:201] op_sel_hi:[1,0]
	v_pk_mul_f32 v[22:23], v[22:23], v[200:201] op_sel_hi:[1,0]
	v_pk_mul_f32 v[20:21], v[20:21], v[200:201] op_sel_hi:[1,0]
	v_pk_mul_f32 v[18:19], v[18:19], v[200:201] op_sel_hi:[1,0]
	v_pk_mul_f32 v[16:17], v[16:17], v[200:201] op_sel_hi:[1,0]
	v_pk_mul_f32 v[14:15], v[14:15], v[200:201] op_sel_hi:[1,0]
	v_pk_mul_f32 v[12:13], v[12:13], v[200:201] op_sel_hi:[1,0]
	v_pk_mul_f32 v[10:11], v[10:11], v[200:201] op_sel_hi:[1,0]
	v_pk_mul_f32 v[8:9], v[8:9], v[200:201] op_sel_hi:[1,0]
	v_pk_mul_f32 v[6:7], v[6:7], v[200:201] op_sel_hi:[1,0]
	v_pk_mul_f32 v[4:5], v[4:5], v[200:201] op_sel_hi:[1,0]
	v_pk_mul_f32 v[2:3], v[2:3], v[200:201] op_sel_hi:[1,0]
	v_pk_mul_f32 v[0:1], v[0:1], v[200:201] op_sel_hi:[1,0]
	v_add_f32_e32 v202, v195, v176
	v_sub_f32_e32 v32, v32, v202
	v_sub_f32_e32 v33, v33, v202
	v_sub_f32_e32 v34, v34, v202
	v_sub_f32_e32 v35, v35, v202
	v_sub_f32_e32 v36, v36, v202
	v_sub_f32_e32 v37, v37, v202
	v_sub_f32_e32 v38, v38, v202
	v_sub_f32_e32 v39, v39, v202
	v_sub_f32_e32 v40, v40, v202
	v_sub_f32_e32 v41, v41, v202
	v_sub_f32_e32 v42, v42, v202
	v_sub_f32_e32 v43, v43, v202
	v_sub_f32_e32 v44, v44, v202
	v_sub_f32_e32 v45, v45, v202
	v_sub_f32_e32 v46, v46, v202
	v_sub_f32_e32 v47, v47, v202
	v_sub_f32_e32 v48, v48, v202
	v_sub_f32_e32 v49, v49, v202
	v_sub_f32_e32 v50, v50, v202
	v_sub_f32_e32 v51, v51, v202
	v_sub_f32_e32 v52, v52, v202
	v_sub_f32_e32 v53, v53, v202
	v_sub_f32_e32 v54, v54, v202
	v_sub_f32_e32 v55, v55, v202
	v_sub_f32_e32 v56, v56, v202
	v_sub_f32_e32 v57, v57, v202
	v_sub_f32_e32 v58, v58, v202
	v_sub_f32_e32 v59, v59, v202
	v_sub_f32_e32 v60, v60, v202
	v_sub_f32_e32 v61, v61, v202
	v_sub_f32_e32 v62, v62, v202
	v_sub_f32_e32 v63, v63, v202
	v_sub_f32_e32 v176, 0, v195
	v_sub_f32_e32 v177, 0, v195
	v_sub_f32_e32 v178, 0, v195
	v_sub_f32_e32 v179, 0, v195
	v_sub_f32_e32 v180, 0, v195
	v_sub_f32_e32 v181, 0, v195
	v_sub_f32_e32 v182, 0, v195
	v_sub_f32_e32 v183, 0, v195
	v_sub_f32_e32 v184, 0, v195
	v_sub_f32_e32 v185, 0, v195
	v_sub_f32_e32 v186, 0, v195
	v_sub_f32_e32 v187, 0, v195
	v_sub_f32_e32 v188, 0, v195
	v_sub_f32_e32 v189, 0, v195
	v_sub_f32_e32 v190, 0, v195
	v_sub_f32_e32 v191, 0, v195
	v_mov_b32_e32 v220, 0x41000000

; #define MFMA(a, b, c) __builtin_amdgcn_mfma_f32_32x32x16_bf16((a), (b), (c), 0, 0, 0)
; DI float fexp2(float x) { return __builtin_amdgcn_exp2f(x); }
; DI f32x16 zero16() { f32x16 z; for (int i = 0; i < 16; ++i) z[i] = 0.f; return z; }
; DI void phase_attn(const Params& p, int hf, bool skipctx, char* smem, int& rot) {
;     ...
;       f32x16 st[2]; st[0] = zero16(); st[1] = zero16();
;       {
;         bf16x8 kf[2][6];
; #pragma unroll
;         for (int kb = 0; kb < 2; ++kb)
; #pragma unroll
;           for (int ks = 0; ks < 6; ++ks) kf[kb][ks] = *(const bf16x8*)(sk + (kb * 32 + r) * KROW + (ks * 16 + h * 8) * 2);
;         __builtin_amdgcn_sched_barrier(0);
; #pragma unroll
;         for (int ks = 0; ks < 6; ++ks)
; #pragma unroll
;           for (int kb = 0; kb < 2; ++kb) st[kb] = MFMA(kf[kb][ks], qf[ks], st[kb]);
;         __builtin_amdgcn_sched_barrier(0);
;       }
;       bf16x8 vf[2][2][2];
; #pragma unroll
;       for (int kb = 0; kb < 2; ++kb)
; #pragma unroll
;         for (int s2 = 0; s2 < 2; ++s2)
; #pragma unroll
;           for (int dvb = 0; dvb < 2; ++dvb) {
;             const char* vp = sv + (dvb * 32 + r) * VROW + (kb * 32 + 16 * s2 + 4 * h) * 2;
;             const s16x4 lo = *(const s16x4*)vp, hi = *(const s16x4*)(vp + 16);
;             vf[kb][s2][dvb] = __builtin_shufflevector(lo, hi, 0, 1, 2, 3, 4, 5, 6, 7);
;           }
;       float mx = st[0][0];
; #pragma unroll
;       for (int i = 0; i < 16; ++i) { mx = fmaxf(mx, st[0][i]); mx = fmaxf(mx, st[1][i]); }
;       if (__any(mx > m_run + 8.f)) {
;         mx = fmaxf(mx, __shfl_xor(mx, 32));
;         const float m_new = fmaxf(m_run, mx);
;         const float alpha = fexp2(m_run - m_new);
;         m_run = m_new;
;         l_run *= alpha;
; #pragma unroll
;         for (int i = 0; i < 16; ++i) { o[0][i] *= alpha; o[1][i] *= alpha; }
;       }
;       float ps = 0.f;
; #pragma unroll
;       for (int kb = 0; kb < 2; ++kb)
; #pragma unroll
;         for (int i = 0; i < 16; ++i) { const float e = fexp2(st[kb][i] - m_run); st[kb][i] = e; ps += e; }
;       l_run += ps;
.LBB0_803:
	v_add_f32_e32 v48, v49, v48
	v_add_f32_e32 v48, v50, v48
	v_add_f32_e32 v48, v51, v48
	v_add_f32_e32 v48, v52, v48
	v_add_f32_e32 v48, v53, v48
	v_add_f32_e32 v48, v54, v48
	v_add_f32_e32 v48, v55, v48
	v_add_f32_e32 v48, v56, v48
	v_add_f32_e32 v48, v57, v48
	v_add_f32_e32 v48, v58, v48
	v_add_f32_e32 v48, v59, v48
	v_add_f32_e32 v48, v60, v48
	v_add_f32_e32 v48, v61, v48
	v_add_f32_e32 v48, v62, v48
	v_add_f32_e32 v48, v63, v48
	v_add_f32_e32 v32, v32, v48
	v_add_f32_e32 v32, v33, v32
	v_add_f32_e32 v32, v34, v32
	v_add_f32_e32 v32, v35, v32
	v_add_f32_e32 v32, v36, v32
	v_add_f32_e32 v32, v37, v32
	v_add_f32_e32 v32, v38, v32
	v_add_f32_e32 v32, v39, v32
	v_add_f32_e32 v32, v40, v32
	v_add_f32_e32 v32, v41, v32
	v_add_f32_e32 v32, v42, v32
	v_add_f32_e32 v32, v43, v32
	v_add_f32_e32 v32, v44, v32
	v_add_f32_e32 v32, v45, v32
	v_add_f32_e32 v32, v46, v32
	v_add_f32_e32 v32, v47, v32
	v_add_f32_e32 v213, v213, v32
	ds_read_b128 v[32:35], v210 offset:44032
	ds_read_b128 v[128:131], v210 offset:44064
	ds_read_b128 v[132:135], v210 offset:44096
	ds_read_b128 v[136:139], v210 offset:44128
	ds_read_b128 v[140:143], v210 offset:44160
	ds_read_b128 v[144:147], v210 offset:44192
	ds_read_b128 v[36:39], v210 offset:50688
	ds_read_b128 v[148:151], v210 offset:50720
	ds_read_b128 v[152:155], v210 offset:50752
	ds_read_b128 v[156:159], v210 offset:50784
	ds_read_b128 v[214:217], v210 offset:50816
	ds_read_b128 v[234:237], v210 offset:50848
	s_waitcnt lgkmcnt(11)
	v_mfma_f32_32x32x16_bf16 v[48:63], v[32:35], v[64:67], v[176:191]
	s_waitcnt lgkmcnt(5)
	v_mfma_f32_32x32x16_bf16 v[32:47], v[36:39], v[64:67], v[176:191]
	v_mfma_f32_32x32x16_bf16 v[48:63], v[128:131], v[68:71], v[48:63]
	s_waitcnt lgkmcnt(4)
	v_mfma_f32_32x32x16_bf16 v[32:47], v[148:151], v[68:71], v[32:47]
	v_mfma_f32_32x32x16_bf16 v[48:63], v[132:135], v[72:75], v[48:63]
	s_waitcnt lgkmcnt(3)
	v_mfma_f32_32x32x16_bf16 v[32:47], v[152:155], v[72:75], v[32:47]
	v_mfma_f32_32x32x16_bf16 v[48:63], v[136:139], v[88:91], v[48:63]
	s_waitcnt lgkmcnt(2)
	v_mfma_f32_32x32x16_bf16 v[32:47], v[156:159], v[88:91], v[32:47]
	v_mfma_f32_32x32x16_bf16 v[48:63], v[140:143], v[96:99], v[48:63]
	s_waitcnt lgkmcnt(1)
	v_mfma_f32_32x32x16_bf16 v[32:47], v[214:217], v[96:99], v[32:47]
	v_mfma_f32_32x32x16_bf16 v[48:63], v[144:147], v[100:103], v[48:63]
	s_waitcnt lgkmcnt(0)
	v_mfma_f32_32x32x16_bf16 v[32:47], v[234:237], v[100:103], v[32:47]
	s_nop 3
	ds_read_b128 v[152:155], v211 offset:52736
	ds_read_b128 v[156:159], v211 offset:44032
	ds_read_b128 v[148:151], v211 offset:44064
	ds_read_b128 v[144:147], v211 offset:52768
	ds_read_b128 v[140:143], v211 offset:44096
	ds_read_b128 v[136:139], v211 offset:52800
	ds_read_b128 v[132:135], v211 offset:44128
	ds_read_b128 v[128:131], v211 offset:52832
	v_max3_f32 v195, v32, v48, v49
	v_max_f32_e32 v195, v195, v33
	v_max3_f32 v195, v195, v50, v34
	v_max3_f32 v195, v195, v51, v35
	v_max3_f32 v195, v195, v52, v36
	v_max3_f32 v195, v195, v53, v37
	v_max3_f32 v195, v195, v54, v38
	v_max3_f32 v195, v195, v55, v39
	v_max3_f32 v195, v195, v56, v40
	v_max3_f32 v195, v195, v57, v41
	v_max3_f32 v195, v195, v58, v42
	v_max3_f32 v195, v195, v59, v43
	v_max3_f32 v195, v195, v60, v44
	v_max3_f32 v195, v195, v61, v45
	v_max3_f32 v195, v195, v62, v46
	v_max3_f32 v215, v195, v63, v47
	v_cmp_gt_f32_e32 vcc, v215, v220
	s_cbranch_vccz .LBB0_805
	v_sub_f32_e32 v215, v215, v176
	v_cmp_lt_i32_e32 vcc, v224, v207
	s_nop 1
	v_cndmask_b32_e32 v195, v205, v224, vcc
	v_lshlrev_b32_e32 v195, 2, v195
	ds_bpermute_b32 v195, v195, v215
	s_waitcnt lgkmcnt(0)
	v_max3_f32 v195, v212, v215, v195
	v_sub_f32_e32 v200, v212, v195
	v_exp_f32_e32 v200, v200
	v_mov_b32_e32 v212, v195
	v_mul_f32_e32 v213, v213, v200
	v_pk_mul_f32 v[30:31], v[30:31], v[200:201] op_sel_hi:[1,0]
	v_pk_mul_f32 v[28:29], v[28:29], v[200:201] op_sel_hi:[1,0]
	v_pk_mul_f32 v[26:27], v[26:27], v[200:201] op_sel_hi:[1,0]
	v_pk_mul_f32 v[24:25], v[24:25], v[200:201] op_sel_hi:[1,0]
	v_pk_mul_f32 v[22:23], v[22:23], v[200:201] op_sel_hi:[1,0]
	v_pk_mul_f32 v[20:21], v[20:21], v[200:201] op_sel_hi:[1,0]
	v_pk_mul_f32 v[18:19], v[18:19], v[200:201] op_sel_hi:[1,0]
	v_pk_mul_f32 v[16:17], v[16:17], v[200:201] op_sel_hi:[1,0]
	v_pk_mul_f32 v[14:15], v[14:15], v[200:201] op_sel_hi:[1,0]
	v_pk_mul_f32 v[12:13], v[12:13], v[200:201] op_sel_hi:[1,0]
	v_pk_mul_f32 v[10:11], v[10:11], v[200:201] op_sel_hi:[1,0]
	v_pk_mul_f32 v[8:9], v[8:9], v[200:201] op_sel_hi:[1,0]
	v_pk_mul_f32 v[6:7], v[6:7], v[200:201] op_sel_hi:[1,0]
	v_pk_mul_f32 v[4:5], v[4:5], v[200:201] op_sel_hi:[1,0]
	v_pk_mul_f32 v[2:3], v[2:3], v[200:201] op_sel_hi:[1,0]
	v_pk_mul_f32 v[0:1], v[0:1], v[200:201] op_sel_hi:[1,0]
	v_add_f32_e32 v202, v195, v176
	v_sub_f32_e32 v32, v32, v202
	v_sub_f32_e32 v33, v33, v202
	v_sub_f32_e32 v34, v34, v202
	v_sub_f32_e32 v35, v35, v202
	v_sub_f32_e32 v36, v36, v202
	v_sub_f32_e32 v37, v37, v202
	v_sub_f32_e32 v38, v38, v202
	v_sub_f32_e32 v39, v39, v202
	v_sub_f32_e32 v40, v40, v202
	v_sub_f32_e32 v41, v41, v202
	v_sub_f32_e32 v42, v42, v202
	v_sub_f32_e32 v43, v43, v202
	v_sub_f32_e32 v44, v44, v202
	v_sub_f32_e32 v45, v45, v202
	v_sub_f32_e32 v46, v46, v202
	v_sub_f32_e32 v47, v47, v202
	v_sub_f32_e32 v48, v48, v202
	v_sub_f32_e32 v49, v49, v202
	v_sub_f32_e32 v50, v50, v202
	v_sub_f32_e32 v51, v51, v202
	v_sub_f32_e32 v52, v52, v202
	v_sub_f32_e32 v53, v53, v202
	v_sub_f32_e32 v54, v54, v202
	v_sub_f32_e32 v55, v55, v202
	v_sub_f32_e32 v56, v56, v202
	v_sub_f32_e32 v57, v57, v202
	v_sub_f32_e32 v58, v58, v202
	v_sub_f32_e32 v59, v59, v202
	v_sub_f32_e32 v60, v60, v202
	v_sub_f32_e32 v61, v61, v202
	v_sub_f32_e32 v62, v62, v202
	v_sub_f32_e32 v63, v63, v202
	v_sub_f32_e32 v176, 0, v195
	v_sub_f32_e32 v177, 0, v195
	v_sub_f32_e32 v178, 0, v195
	v_sub_f32_e32 v179, 0, v195
	v_sub_f32_e32 v180, 0, v195
	v_sub_f32_e32 v181, 0, v195
	v_sub_f32_e32 v182, 0, v195
	v_sub_f32_e32 v183, 0, v195
	v_sub_f32_e32 v184, 0, v195
	v_sub_f32_e32 v185, 0, v195
	v_sub_f32_e32 v186, 0, v195
	v_sub_f32_e32 v187, 0, v195
	v_sub_f32_e32 v188, 0, v195
	v_sub_f32_e32 v189, 0, v195
	v_sub_f32_e32 v190, 0, v195
	v_sub_f32_e32 v191, 0, v195
	v_mov_b32_e32 v220, 0x41000000
; #define MFMA(a, b, c) __builtin_amdgcn_mfma_f32_32x32x16_bf16((a), (b), (c), 0, 0, 0)
; DI void phase_attn(const Params& p, int hf, bool skipctx, char* smem, int& rot) {
;     ...
;       f32x16 st[2]; st[0] = zero16(); st[1] = zero16();
;       {
;         bf16x8 kf[2][6];
; #pragma unroll
;         for (int kb = 0; kb < 2; ++kb)
; #pragma unroll
;           for (int ks = 0; ks < 6; ++ks) kf[kb][ks] = *(const bf16x8*)(sk + (kb * 32 + r) * KROW + (ks * 16 + h * 8) * 2);
;         __builtin_amdgcn_sched_barrier(0);
; #pragma unroll
;         for (int ks = 0; ks < 6; ++ks)
; #pragma unroll
;           for (int kb = 0; kb < 2; ++kb) st[kb] = MFMA(kf[kb][ks], qf[ks], st[kb]);
;         __builtin_amdgcn_sched_barrier(0);
;       }
;       bf16x8 vf[2][2][2];
; #pragma unroll
;       for (int kb = 0; kb < 2; ++kb)
; #pragma unroll
;         for (int s2 = 0; s2 < 2; ++s2)
; #pragma unroll
;           for (int dvb = 0; dvb < 2; ++dvb) {
;             const char* vp = sv + (dvb * 32 + r) * VROW + (kb * 32 + 16 * s2 + 4 * h) * 2;
;             const s16x4 lo = *(const s16x4*)vp, hi = *(const s16x4*)(vp + 16);
;             vf[kb][s2][dvb] = __builtin_shufflevector(lo, hi, 0, 1, 2, 3, 4, 5, 6, 7);
;           }
;       float mx = st[0][0];
; #pragma unroll
;       for (int i = 0; i < 16; ++i) { mx = fmaxf(mx, st[0][i]); mx = fmaxf(mx, st[1][i]); }
;       if (__any(mx > m_run + 8.f)) {
;         mx = fmaxf(mx, __shfl_xor(mx, 32));
;         const float m_new = fmaxf(m_run, mx);
;         const float alpha = fexp2(m_run - m_new);
;         m_run = m_new;
;         l_run *= alpha;
; #pragma unroll
;         for (int i = 0; i < 16; ++i) { o[0][i] *= alpha; o[1][i] *= alpha; }
;       }
;       float ps = 0.f;
; #pragma unroll
;       for (int kb = 0; kb < 2; ++kb)
; #pragma unroll
;         for (int i = 0; i < 16; ++i) { const float e = fexp2(st[kb][i] - m_run); st[kb][i] = e; ps += e; }
;       l_run += ps;
; #pragma unroll
;       for (int kb = 0; kb < 2; ++kb)
; #pragma unroll
;         for (int s2 = 0; s2 < 2; ++s2) {
;           const bf16x8 pb = pack8(st[kb][8 * s2 + 0], st[kb][8 * s2 + 1], st[kb][8 * s2 + 2], st[kb][8 * s2 + 3], st[kb][8 * s2 + 4], st[kb][8 * s2 + 5], st[kb][8 * s2 + 6], st[kb][8 * s2 + 7]);
; #pragma unroll
;           for (int dvb = 0; dvb < 2; ++dvb) o[dvb] = MFMA(vf[kb][s2][dvb], pb, o[dvb]);
;         }
.LBB0_805:
	v_exp_f32_e32 v48, v48
	v_exp_f32_e32 v49, v49
	v_exp_f32_e32 v50, v50
	v_exp_f32_e32 v51, v51
	v_exp_f32_e32 v52, v52
	v_add_f32_e32 v195, v49, v48
	v_exp_f32_e32 v53, v53
	v_add_f32_e32 v195, v50, v195
	v_exp_f32_e32 v54, v54
	v_add_f32_e32 v195, v51, v195
	v_exp_f32_e32 v55, v55
	v_add_f32_e32 v195, v52, v195
	v_exp_f32_e32 v56, v56
	v_add_f32_e32 v195, v53, v195
	v_exp_f32_e32 v57, v57
	v_add_f32_e32 v195, v54, v195
	v_exp_f32_e32 v58, v58
	v_add_f32_e32 v195, v55, v195
	v_exp_f32_e32 v59, v59
	v_add_f32_e32 v195, v56, v195
	v_exp_f32_e32 v60, v60
	v_add_f32_e32 v195, v57, v195
	v_exp_f32_e32 v61, v61
	v_add_f32_e32 v195, v58, v195
	v_exp_f32_e32 v62, v62
	v_add_f32_e32 v195, v59, v195
	v_exp_f32_e32 v63, v63
	v_add_f32_e32 v195, v60, v195
	v_exp_f32_e32 v200, v32
	v_add_f32_e32 v195, v61, v195
	v_exp_f32_e32 v201, v33
	v_add_f32_e32 v32, v62, v195
	v_exp_f32_e32 v195, v34
	v_add_f32_e32 v32, v63, v32
	v_exp_f32_e32 v202, v35
	v_add_f32_e32 v32, v200, v32
	v_exp_f32_e32 v36, v36
	v_add_f32_e32 v32, v201, v32
	v_exp_f32_e32 v37, v37
	v_add_f32_e32 v32, v195, v32
	v_add_f32_e32 v32, v202, v32
	v_add_f32_e32 v32, v36, v32
	v_add_f32_e32 v203, v37, v32
	v_cvt_pk_bf16_f32 v32, v48, v49
	v_cvt_pk_bf16_f32 v33, v50, v51
	v_cvt_pk_bf16_f32 v34, v52, v53
	v_cvt_pk_bf16_f32 v35, v54, v55
	v_exp_f32_e32 v38, v38
	s_waitcnt lgkmcnt(6)
	v_mfma_f32_32x32x16_bf16 v[16:31], v[156:159], v[32:35], v[16:31]
	v_exp_f32_e32 v39, v39
	v_exp_f32_e32 v40, v40
	v_add_f32_e32 v48, v38, v203
	v_exp_f32_e32 v42, v42
	v_mfma_f32_32x32x16_bf16 v[0:15], v[152:155], v[32:35], v[0:15]
	v_exp_f32_e32 v41, v41
	v_cvt_pk_bf16_f32 v32, v56, v57
	v_cvt_pk_bf16_f32 v33, v58, v59
	v_cvt_pk_bf16_f32 v34, v60, v61
	v_cvt_pk_bf16_f32 v35, v62, v63
	v_add_f32_e32 v48, v39, v48
	s_waitcnt lgkmcnt(5)
	v_mfma_f32_32x32x16_bf16 v[16:31], v[148:151], v[32:35], v[16:31]
	v_exp_f32_e32 v43, v43
	v_add_f32_e32 v48, v40, v48
	v_exp_f32_e32 v44, v44
	v_add_f32_e32 v48, v41, v48
	s_waitcnt lgkmcnt(4)
	v_mfma_f32_32x32x16_bf16 v[0:15], v[144:147], v[32:35], v[0:15]
	v_add_f32_e32 v32, v42, v48
	v_add_f32_e32 v32, v43, v32
	v_add_f32_e32 v48, v44, v32
	v_cvt_pk_bf16_f32 v32, v200, v201
	v_cvt_pk_bf16_f32 v33, v195, v202
	v_cvt_pk_bf16_f32 v34, v36, v37
	v_cvt_pk_bf16_f32 v35, v38, v39
	v_exp_f32_e32 v36, v45
	s_waitcnt lgkmcnt(3)
	v_mfma_f32_32x32x16_bf16 v[16:31], v[140:143], v[32:35], v[16:31]
	v_exp_f32_e32 v37, v46
	v_exp_f32_e32 v38, v47
	v_add_f32_e32 v39, v36, v48
	s_waitcnt lgkmcnt(2)
	v_mfma_f32_32x32x16_bf16 v[0:15], v[136:139], v[32:35], v[0:15]
	v_add_f32_e32 v32, v37, v39
	v_add_f32_e32 v32, v38, v32
	v_add_f32_e32 v213, v213, v32
	v_cvt_pk_bf16_f32 v32, v40, v41
	v_cvt_pk_bf16_f32 v33, v42, v43
	v_cvt_pk_bf16_f32 v34, v44, v36
	v_cvt_pk_bf16_f32 v35, v37, v38
	s_waitcnt lgkmcnt(1)
	s_nop 0
	v_mfma_f32_32x32x16_bf16 v[16:31], v[132:135], v[32:35], v[16:31]
	ds_read_b128 v[36:39], v210 offset:57344
	ds_read_b128 v[132:135], v210 offset:57376
	ds_read_b128 v[136:139], v210 offset:57408
	ds_read_b128 v[140:143], v210 offset:57440
	ds_read_b128 v[144:147], v210 offset:57472
	ds_read_b128 v[148:151], v210 offset:57504
	ds_read_b128 v[40:43], v210 offset:64000
	ds_read_b128 v[152:155], v210 offset:64032
	ds_read_b128 v[156:159], v210 offset:64064
	ds_read_b128 v[216:219], v210 offset:64096
	ds_read_b128 v[234:237], v210 offset:64128
	ds_read_b128 v[238:241], v210 offset:64160
	s_waitcnt lgkmcnt(12)
	v_mfma_f32_32x32x16_bf16 v[0:15], v[128:131], v[32:35], v[0:15]
	s_waitcnt lgkmcnt(11)
	v_mfma_f32_32x32x16_bf16 v[48:63], v[36:39], v[64:67], v[176:191]
	s_waitcnt lgkmcnt(5)
	v_mfma_f32_32x32x16_bf16 v[32:47], v[40:43], v[64:67], v[176:191]
	v_mfma_f32_32x32x16_bf16 v[48:63], v[132:135], v[68:71], v[48:63]
	s_waitcnt lgkmcnt(4)
	v_mfma_f32_32x32x16_bf16 v[32:47], v[152:155], v[68:71], v[32:47]
	v_mfma_f32_32x32x16_bf16 v[48:63], v[136:139], v[72:75], v[48:63]
	s_waitcnt lgkmcnt(3)
	v_mfma_f32_32x32x16_bf16 v[32:47], v[156:159], v[72:75], v[32:47]
	v_mfma_f32_32x32x16_bf16 v[48:63], v[140:143], v[88:91], v[48:63]
	s_waitcnt lgkmcnt(2)
	v_mfma_f32_32x32x16_bf16 v[32:47], v[216:219], v[88:91], v[32:47]
	v_mfma_f32_32x32x16_bf16 v[48:63], v[144:147], v[96:99], v[48:63]
	s_waitcnt lgkmcnt(1)
	v_mfma_f32_32x32x16_bf16 v[32:47], v[234:237], v[96:99], v[32:47]
	v_mfma_f32_32x32x16_bf16 v[48:63], v[148:151], v[100:103], v[48:63]
	s_waitcnt lgkmcnt(0)
	v_mfma_f32_32x32x16_bf16 v[32:47], v[238:241], v[100:103], v[32:47]
	s_nop 3
	ds_read_b128 v[152:155], v211 offset:52864
	ds_read_b128 v[156:159], v211 offset:44160
	ds_read_b128 v[148:151], v211 offset:44192
	ds_read_b128 v[144:147], v211 offset:52896
	ds_read_b128 v[140:143], v211 offset:44224
	ds_read_b128 v[136:139], v211 offset:52928
	ds_read_b128 v[132:135], v211 offset:44256
	ds_read_b128 v[128:131], v211 offset:52960
	v_max3_f32 v195, v32, v48, v49
	v_max_f32_e32 v195, v195, v33
	v_max3_f32 v195, v195, v50, v34
	v_max3_f32 v195, v195, v51, v35
	v_max3_f32 v195, v195, v52, v36
	v_max3_f32 v195, v195, v53, v37
	v_max3_f32 v195, v195, v54, v38
	v_max3_f32 v195, v195, v55, v39
	v_max3_f32 v195, v195, v56, v40
	v_max3_f32 v195, v195, v57, v41
	v_max3_f32 v195, v195, v58, v42
	v_max3_f32 v195, v195, v59, v43
	v_max3_f32 v195, v195, v60, v44
	v_max3_f32 v195, v195, v61, v45
	v_max3_f32 v195, v195, v62, v46
	v_max3_f32 v215, v195, v63, v47
	v_cmp_gt_f32_e32 vcc, v215, v220
	s_cbranch_vccz .LBB0_807
; DI float fexp2(float x) { return __builtin_amdgcn_exp2f(x); }
; DI void phase_attn(const Params& p, int hf, bool skipctx, char* smem, int& rot) {
;     ...
;       if (__any(mx > m_run + 8.f)) {
;         mx = fmaxf(mx, __shfl_xor(mx, 32));
;         const float m_new = fmaxf(m_run, mx);
;         const float alpha = fexp2(m_run - m_new);
;         m_run = m_new;
;         l_run *= alpha;
; #pragma unroll
;         for (int i = 0; i < 16; ++i) { o[0][i] *= alpha; o[1][i] *= alpha; }
;       }
	v_sub_f32_e32 v215, v215, v176
	v_cmp_lt_i32_e32 vcc, v224, v207
	s_nop 1
	v_cndmask_b32_e32 v195, v205, v224, vcc
	v_lshlrev_b32_e32 v195, 2, v195
	ds_bpermute_b32 v195, v195, v215
	s_waitcnt lgkmcnt(0)
	v_max3_f32 v195, v212, v215, v195
	v_sub_f32_e32 v200, v212, v195
	v_exp_f32_e32 v200, v200
	v_mov_b32_e32 v212, v195
	v_mul_f32_e32 v213, v213, v200
	v_pk_mul_f32 v[30:31], v[30:31], v[200:201] op_sel_hi:[1,0]
	v_pk_mul_f32 v[28:29], v[28:29], v[200:201] op_sel_hi:[1,0]
	v_pk_mul_f32 v[26:27], v[26:27], v[200:201] op_sel_hi:[1,0]
	v_pk_mul_f32 v[24:25], v[24:25], v[200:201] op_sel_hi:[1,0]
	v_pk_mul_f32 v[22:23], v[22:23], v[200:201] op_sel_hi:[1,0]
	v_pk_mul_f32 v[20:21], v[20:21], v[200:201] op_sel_hi:[1,0]
	v_pk_mul_f32 v[18:19], v[18:19], v[200:201] op_sel_hi:[1,0]
	v_pk_mul_f32 v[16:17], v[16:17], v[200:201] op_sel_hi:[1,0]
	v_pk_mul_f32 v[14:15], v[14:15], v[200:201] op_sel_hi:[1,0]
	v_pk_mul_f32 v[12:13], v[12:13], v[200:201] op_sel_hi:[1,0]
	v_pk_mul_f32 v[10:11], v[10:11], v[200:201] op_sel_hi:[1,0]
	v_pk_mul_f32 v[8:9], v[8:9], v[200:201] op_sel_hi:[1,0]
	v_pk_mul_f32 v[6:7], v[6:7], v[200:201] op_sel_hi:[1,0]
	v_pk_mul_f32 v[4:5], v[4:5], v[200:201] op_sel_hi:[1,0]
	v_pk_mul_f32 v[2:3], v[2:3], v[200:201] op_sel_hi:[1,0]
	v_pk_mul_f32 v[0:1], v[0:1], v[200:201] op_sel_hi:[1,0]
	v_add_f32_e32 v202, v195, v176
	v_sub_f32_e32 v32, v32, v202
	v_sub_f32_e32 v33, v33, v202
	v_sub_f32_e32 v34, v34, v202
	v_sub_f32_e32 v35, v35, v202
	v_sub_f32_e32 v36, v36, v202
	v_sub_f32_e32 v37, v37, v202
	v_sub_f32_e32 v38, v38, v202
	v_sub_f32_e32 v39, v39, v202
	v_sub_f32_e32 v40, v40, v202
	v_sub_f32_e32 v41, v41, v202
	v_sub_f32_e32 v42, v42, v202
	v_sub_f32_e32 v43, v43, v202
	v_sub_f32_e32 v44, v44, v202
	v_sub_f32_e32 v45, v45, v202
	v_sub_f32_e32 v46, v46, v202
	v_sub_f32_e32 v47, v47, v202
	v_sub_f32_e32 v48, v48, v202
	v_sub_f32_e32 v49, v49, v202
	v_sub_f32_e32 v50, v50, v202
	v_sub_f32_e32 v51, v51, v202
	v_sub_f32_e32 v52, v52, v202
	v_sub_f32_e32 v53, v53, v202
	v_sub_f32_e32 v54, v54, v202
	v_sub_f32_e32 v55, v55, v202
	v_sub_f32_e32 v56, v56, v202
	v_sub_f32_e32 v57, v57, v202
	v_sub_f32_e32 v58, v58, v202
	v_sub_f32_e32 v59, v59, v202
	v_sub_f32_e32 v60, v60, v202
	v_sub_f32_e32 v61, v61, v202
	v_sub_f32_e32 v62, v62, v202
	v_sub_f32_e32 v63, v63, v202
	v_sub_f32_e32 v176, 0, v195
	v_sub_f32_e32 v177, 0, v195
	v_sub_f32_e32 v178, 0, v195
	v_sub_f32_e32 v179, 0, v195
	v_sub_f32_e32 v180, 0, v195
	v_sub_f32_e32 v181, 0, v195
	v_sub_f32_e32 v182, 0, v195
	v_sub_f32_e32 v183, 0, v195
	v_sub_f32_e32 v184, 0, v195
	v_sub_f32_e32 v185, 0, v195
	v_sub_f32_e32 v186, 0, v195
	v_sub_f32_e32 v187, 0, v195
	v_sub_f32_e32 v188, 0, v195
	v_sub_f32_e32 v189, 0, v195
	v_sub_f32_e32 v190, 0, v195
	v_sub_f32_e32 v191, 0, v195
	v_mov_b32_e32 v220, 0x41000000

; DI float fexp2(float x) { return __builtin_amdgcn_exp2f(x); }
; DI void phase_attn(const Params& p, int hf, bool skipctx, char* smem, int& rot) {
;     ...
;       float ps = 0.f;
; #pragma unroll
;       for (int kb = 0; kb < 2; ++kb)
; #pragma unroll
;         for (int i = 0; i < 16; ++i) { const float e = fexp2(st[kb][i] - m_run); st[kb][i] = e; ps += e; }
;       l_run += ps;
;     ...
;       __syncthreads();
;     }
.LBB0_809:
	v_add_f32_e32 v48, v49, v48
	v_add_f32_e32 v48, v50, v48
	v_add_f32_e32 v48, v51, v48
	v_add_f32_e32 v48, v52, v48
	v_add_f32_e32 v48, v53, v48
	v_add_f32_e32 v48, v54, v48
	v_add_f32_e32 v48, v55, v48
	v_add_f32_e32 v48, v56, v48
	v_add_f32_e32 v48, v57, v48
	v_add_f32_e32 v48, v58, v48
	v_add_f32_e32 v48, v59, v48
	v_add_f32_e32 v48, v60, v48
	v_add_f32_e32 v48, v61, v48
	v_add_f32_e32 v48, v62, v48
	v_add_f32_e32 v48, v63, v48
	v_add_f32_e32 v32, v32, v48
	v_add_f32_e32 v32, v33, v32
	v_add_f32_e32 v32, v34, v32
	v_add_f32_e32 v32, v35, v32
	v_add_f32_e32 v32, v36, v32
	v_add_f32_e32 v32, v37, v32
	v_add_f32_e32 v32, v38, v32
	v_add_f32_e32 v32, v39, v32
	v_add_f32_e32 v32, v40, v32
	v_add_f32_e32 v32, v41, v32
	v_add_f32_e32 v32, v42, v32
	v_add_f32_e32 v32, v43, v32
	v_add_f32_e32 v32, v44, v32
	v_add_f32_e32 v32, v45, v32
	v_add_f32_e32 v32, v46, v32
	v_add_f32_e32 v32, v47, v32
	v_add_f32_e32 v213, v213, v32
	v_lshl_add_u64 v[166:167], v[166:167], 0, s[24:25]
	v_lshl_add_u64 v[168:169], v[168:169], 0, s[24:25]
	v_lshl_add_u64 v[170:171], v[170:171], 0, s[30:31]
	v_lshl_add_u64 v[172:173], v[172:173], 0, s[30:31]
	v_lshl_add_u64 v[174:175], v[174:175], 0, s[30:31]
	s_and_b64 vcc, exec, s[26:27]
	s_waitcnt lgkmcnt(0)
	s_barrier
	s_cbranch_vccnz .LBB0_770
	s_mov_b32 s4, s15
	s_branch .LBB0_795
